# P0 weight-transpose loops unrolled x2 (two items of loads in flight per wave) on top of v66
# baseline (speedup 1.0000x reference)
; #define LAS __attribute__((address_space(3)))
; __device__ __forceinline__ void transpose_items(const float* W, int K, int ldw, int src0, int ncols, int blk, int mul, int add, bf16* WT, LAS float* scr, int gw, int NGW, int lane) {
;     const int nblk = ncols / 32, nitems = (K / 64) * nblk;
;     for (int it = gw; it < nitems; it += NGW) {
;         const int kb = it / nblk, nb = it - kb * nblk, k0 = 64 * kb, nl = 32 * nb;
;         const int drow = (nl / blk) * mul + (nl % blk) + add;
;         const float* src = W + (size_t)k0 * ldw + src0 + nl + (lane & 31);
;         float tv[32];
; #pragma unroll
;         for (int i = 0; i < 32; ++i) tv[i] = src[(size_t)(2 * i + (lane >> 5)) * ldw];
.LBB0_88:
	v_readlane_b32 s0, v254, 0
	s_lshl_b32 s0, s0, 14
	s_add_i32 s10, s0, 0
	s_cmpk_lt_i32 s74, 0x4000
	s_cselect_b64 s[0:1], -1, 0
	s_cmpk_gt_i32 s74, 0x3fff
	s_cbranch_scc1 .LBB0_91
	v_lshlrev_b32_e32 v2, 3, v0
	v_and_b32_e32 v2, 56, v2
	v_mov_b32_e32 v3, 0
	v_lshrrev_b32_e32 v64, 3, v198
	v_mul_u32_u24_e32 v8, 0x84, v2
	v_lshlrev_b32_e32 v2, 1, v2
	v_lshl_add_u64 v[4:5], s[78:79], 0, v[2:3]
	v_lshlrev_b32_e32 v2, 2, v64
	v_lshrrev_b32_e32 v7, 5, v198
	v_add3_u32 v65, s10, v8, v2
	s_movk_i32 s6, 0x5830
	v_mov_b32_e32 v8, 0x2c180
	v_mad_u32_u24 v10, v7, s6, v8
	v_mov_b32_e32 v8, 0x371e0
	v_mad_u32_u24 v12, v7, s6, v8
	v_mov_b32_e32 v8, 0x42240
	v_mad_u32_u24 v14, v7, s6, v8
	v_mov_b32_e32 v8, 0x4d2a0
	v_mad_u32_u24 v16, v7, s6, v8
	v_mov_b32_e32 v8, 0x58300
	v_mad_u32_u24 v18, v7, s6, v8
	v_mov_b32_e32 v8, 0x63360
	v_mad_u32_u24 v20, v7, s6, v8
	v_mov_b32_e32 v8, 0x6e3c0
	v_mad_u32_u24 v22, v7, s6, v8
	v_mov_b32_e32 v8, 0x79420
	v_mad_u32_u24 v24, v7, s6, v8
	v_mov_b32_e32 v8, 0x84480
	v_mad_u32_u24 v26, v7, s6, v8
	v_mov_b32_e32 v8, 0x8f4e0
	v_mad_u32_u24 v28, v7, s6, v8
	v_mov_b32_e32 v8, 0x9a540
	v_mad_u32_u24 v30, v7, s6, v8
	v_mov_b32_e32 v8, 0xa55a0
	v_mad_u32_u24 v32, v7, s6, v8
	v_mov_b32_e32 v8, 0xb0600
	v_mad_u32_u24 v34, v7, s6, v8
	v_mov_b32_e32 v8, 0xbb660
	v_mad_u32_u24 v36, v7, s6, v8
	v_mov_b32_e32 v8, 0xc66c0
	v_mad_u32_u24 v38, v7, s6, v8
	v_mov_b32_e32 v8, 0xd1720
	v_mad_u32_u24 v40, v7, s6, v8
	v_mov_b32_e32 v8, 0xdc780
	v_mad_u32_u24 v42, v7, s6, v8
	v_mov_b32_e32 v8, 0xe77e0
	v_mad_u32_u24 v44, v7, s6, v8
	v_mov_b32_e32 v8, 0xf2840
	v_mad_u32_u24 v46, v7, s6, v8
	v_mov_b32_e32 v8, 0xfd8a0
	v_mad_u32_u24 v48, v7, s6, v8
	v_mov_b32_e32 v8, 0x108900
	v_mad_u32_u24 v50, v7, s6, v8
	v_mov_b32_e32 v8, 0x113960
	v_mad_u32_u24 v52, v7, s6, v8
	v_mov_b32_e32 v8, 0x11e9c0
	v_mad_u32_u24 v54, v7, s6, v8
	v_mov_b32_e32 v8, 0x129a20
	v_mad_u32_u24 v56, v7, s6, v8
	v_mov_b32_e32 v8, 0x134a80
	v_mad_u32_u24 v58, v7, s6, v8
	v_mov_b32_e32 v8, 0x13fae0
	v_mad_u32_u24 v60, v7, s6, v8
	v_mov_b32_e32 v8, 0x14ab40
	v_and_b32_e32 v6, 31, v0
	v_mad_u32_u24 v62, v7, s6, v8
	v_mov_b32_e32 v8, 0x155ba0
	v_readlane_b32 s7, v254, 0
	v_lshl_add_u32 v9, v6, 2, s10
	v_mul_u32_u24_e32 v2, 0x5830, v7
	v_mad_u32_u24 v70, v7, s6, v8
	v_mul_u32_u24_e32 v7, 0x84, v7
	s_lshl_b32 s6, s56, 8
	s_lshl_b32 s7, s7, 5
	v_readlane_b32 s36, v254, 7
	v_or_b32_e32 v66, 8, v64
	v_or_b32_e32 v67, 16, v64
	v_or_b32_e32 v68, 24, v64
	s_add_i32 s11, s6, s7
	s_lshl_b32 s12, s72, 8
	v_lshlrev_b32_e32 v6, 2, v6
	v_lshlrev_b32_e32 v8, 2, v2
	s_mov_b32 s13, 0x2c000
	s_mov_b32 s14, 0x58000
	s_mov_b32 s15, 0x84000
	v_lshlrev_b32_e32 v10, 2, v10
	v_lshlrev_b32_e32 v12, 2, v12
	v_lshlrev_b32_e32 v14, 2, v14
	v_lshlrev_b32_e32 v16, 2, v16
	v_lshlrev_b32_e32 v18, 2, v18
	v_lshlrev_b32_e32 v20, 2, v20
	v_lshlrev_b32_e32 v22, 2, v22
	v_lshlrev_b32_e32 v24, 2, v24
	v_lshlrev_b32_e32 v26, 2, v26
	v_lshlrev_b32_e32 v28, 2, v28
	v_lshlrev_b32_e32 v30, 2, v30
	v_lshlrev_b32_e32 v32, 2, v32
	v_lshlrev_b32_e32 v34, 2, v34
	v_lshlrev_b32_e32 v36, 2, v36
	v_lshlrev_b32_e32 v38, 2, v38
	v_lshlrev_b32_e32 v40, 2, v40
	v_lshlrev_b32_e32 v42, 2, v42
	v_lshlrev_b32_e32 v2, 2, v44
	v_lshlrev_b32_e32 v44, 2, v46
	v_lshlrev_b32_e32 v46, 2, v48
	v_lshlrev_b32_e32 v48, 2, v50
	v_lshlrev_b32_e32 v50, 2, v52
	v_lshlrev_b32_e32 v52, 2, v54
	v_lshlrev_b32_e32 v54, 2, v56
	v_lshlrev_b32_e32 v56, 2, v58
	v_lshlrev_b32_e32 v58, 2, v60
	v_lshlrev_b32_e32 v60, 2, v62
	v_lshlrev_b32_e32 v62, 2, v70
	v_add_u32_e32 v69, v9, v7
	v_mov_b32_e32 v7, v3
	v_mov_b32_e32 v9, v3
	v_mov_b32_e32 v11, v3
	v_mov_b32_e32 v13, v3
	v_mov_b32_e32 v15, v3
	v_mov_b32_e32 v17, v3
	v_mov_b32_e32 v19, v3
	v_mov_b32_e32 v21, v3
	v_mov_b32_e32 v23, v3
	v_mov_b32_e32 v25, v3
	v_mov_b32_e32 v27, v3
	v_mov_b32_e32 v29, v3
	v_mov_b32_e32 v31, v3
	v_mov_b32_e32 v33, v3
	v_mov_b32_e32 v35, v3
	v_mov_b32_e32 v37, v3
	v_mov_b32_e32 v39, v3
	v_mov_b32_e32 v41, v3
	v_mov_b32_e32 v43, v3
	s_mov_b32 s24, s74
	v_readlane_b32 s40, v254, 11
	v_readlane_b32 s41, v254, 12
	v_readlane_b32 s37, v254, 8
	v_readlane_b32 s38, v254, 9
	v_readlane_b32 s39, v254, 10
	v_readlane_b32 s42, v254, 13
	v_readlane_b32 s43, v254, 14
	v_readlane_b32 s44, v254, 15
	v_readlane_b32 s45, v254, 16
	v_readlane_b32 s46, v254, 17
	v_readlane_b32 s47, v254, 18
	v_readlane_b32 s48, v254, 19
	v_readlane_b32 s49, v254, 20
	v_readlane_b32 s50, v254, 21
	v_readlane_b32 s51, v254, 22
	v_mov_b32_e32 v200, v44
	v_mov_b32_e32 v202, v46
	v_mov_b32_e32 v204, v48
	v_mov_b32_e32 v206, v50
	v_mov_b32_e32 v208, v52
	v_mov_b32_e32 v210, v54
	v_mov_b32_e32 v212, v56
	v_mov_b32_e32 v214, v58
	v_mov_b32_e32 v216, v60
	v_mov_b32_e32 v218, v62
; #define LAS __attribute__((address_space(3)))
; #define LDS_WAIT() asm volatile("s_waitcnt lgkmcnt(0)" ::: "memory")
; __device__ __forceinline__ unsigned pk2(float lo, float hi) { const f32x2c v = {lo, hi}; return __builtin_bit_cast(unsigned, __builtin_convertvector(v, bf16x2c)); }
; __device__ __forceinline__ void transpose_items(const float* W, int K, int ldw, int src0, int ncols, int blk, int mul, int add, bf16* WT, LAS float* scr, int gw, int NGW, int lane) {
;     ...
;     for (int it = gw; it < nitems; it += NGW) {
;         const int kb = it / nblk, nb = it - kb * nblk, k0 = 64 * kb, nl = 32 * nb;
;         const int drow = (nl / blk) * mul + (nl % blk) + add;
;         const float* src = W + (size_t)k0 * ldw + src0 + nl + (lane & 31);
;         float tv[32];
; #pragma unroll
;         for (int i = 0; i < 32; ++i) tv[i] = src[(size_t)(2 * i + (lane >> 5)) * ldw];
; #pragma unroll
;         for (int i = 0; i < 32; ++i) scr[(2 * i + (lane >> 5)) * 33 + (lane & 31)] = tv[i];
;         LDS_WAIT(); asm volatile("" ::: "memory");
;         const int c = lane & 7;
; #pragma unroll
;         for (int j = 0; j < 4; ++j) { const int n = (lane >> 3) + 8 * j; const LAS float* s = scr + (8 * c) * 33 + n;
;             v4u o; o.x = pk2(s[0 * 33], s[1 * 33]); o.y = pk2(s[2 * 33], s[3 * 33]); o.z = pk2(s[4 * 33], s[5 * 33]); o.w = pk2(s[6 * 33], s[7 * 33]);
;             *(v4u*)(WT + (size_t)(drow + n) * K + k0 + 8 * c) = o; }
.LBB0_90:
	s_add_i32 s32, s24, s76
	s_cmpk_lt_i32 s32, 0x4000
	s_cbranch_scc0 .Ltp90_single
	s_ashr_i32 s6, s24, 31
	s_lshr_b32 s6, s6, 24
	s_add_i32 s6, s24, s6
	s_ashr_i32 s6, s6, 8
	s_lshl_b32 s8, s6, 6
	s_lshl_b32 s7, s6, 13
	s_mul_i32 s25, s6, 0x583000
	s_sub_i32 s6, s11, s7
	s_ashr_i32 s9, s8, 31
	s_mul_hi_i32 s7, s8, 0x160c0
	s_add_u32 s25, s40, s25
	s_addc_u32 s28, s41, s7
	s_ashr_i32 s7, s6, 31
	s_lshl_b64 s[26:27], s[6:7], 2
	s_add_u32 s26, s25, s26
	s_addc_u32 s27, s28, s27
	v_lshl_add_u64 v[70:71], s[26:27], 0, v[6:7]
	v_lshl_add_u64 v[72:73], v[70:71], 0, v[8:9]
	v_add_co_u32_e32 v128, vcc, s13, v72
	v_mov_b32_e32 v45, v3
	s_nop 0
	v_addc_co_u32_e32 v129, vcc, 0, v73, vcc
	v_add_co_u32_e32 v130, vcc, s14, v72
	v_mov_b32_e32 v47, v3
	s_nop 0
	v_addc_co_u32_e32 v131, vcc, 0, v73, vcc
	v_mov_b32_e32 v49, v3
	v_mov_b32_e32 v51, v3
	v_mov_b32_e32 v53, v3
	v_mov_b32_e32 v55, v3
	v_mov_b32_e32 v57, v3
	v_mov_b32_e32 v59, v3
	v_mov_b32_e32 v61, v3
	v_mov_b32_e32 v63, v3
	v_lshl_add_u64 v[80:81], v[70:71], 0, v[16:17]
	v_lshl_add_u64 v[82:83], v[70:71], 0, v[18:19]
	v_lshl_add_u64 v[84:85], v[70:71], 0, v[20:21]
	v_lshl_add_u64 v[94:95], v[70:71], 0, v[30:31]
	v_lshl_add_u64 v[96:97], v[70:71], 0, v[32:33]
	v_lshl_add_u64 v[98:99], v[70:71], 0, v[34:35]
	v_lshl_add_u64 v[100:101], v[70:71], 0, v[36:37]
	v_lshl_add_u64 v[102:103], v[70:71], 0, v[38:39]
	v_lshl_add_u64 v[104:105], v[70:71], 0, v[40:41]
	v_lshl_add_u64 v[106:107], v[70:71], 0, v[42:43]
	v_lshl_add_u64 v[108:109], v[70:71], 0, v[2:3]
	v_lshl_add_u64 v[110:111], v[70:71], 0, v[44:45]
	v_add_co_u32_e32 v132, vcc, s15, v72
	v_lshl_add_u64 v[74:75], v[70:71], 0, v[10:11]
	v_lshl_add_u64 v[76:77], v[70:71], 0, v[12:13]
	v_lshl_add_u64 v[78:79], v[70:71], 0, v[14:15]
	v_lshl_add_u64 v[86:87], v[70:71], 0, v[22:23]
	v_lshl_add_u64 v[88:89], v[70:71], 0, v[24:25]
	v_lshl_add_u64 v[90:91], v[70:71], 0, v[26:27]
	v_lshl_add_u64 v[92:93], v[70:71], 0, v[28:29]
	v_lshl_add_u64 v[112:113], v[70:71], 0, v[46:47]
	v_lshl_add_u64 v[114:115], v[70:71], 0, v[48:49]
	v_lshl_add_u64 v[116:117], v[70:71], 0, v[50:51]
	v_lshl_add_u64 v[118:119], v[70:71], 0, v[52:53]
	v_lshl_add_u64 v[120:121], v[70:71], 0, v[54:55]
	v_lshl_add_u64 v[122:123], v[70:71], 0, v[56:57]
	v_lshl_add_u64 v[124:125], v[70:71], 0, v[58:59]
	v_lshl_add_u64 v[126:127], v[70:71], 0, v[60:61]
	v_lshl_add_u64 v[70:71], v[70:71], 0, v[62:63]
	v_addc_co_u32_e32 v133, vcc, 0, v73, vcc
	global_load_dword v45, v[82:83], off
	global_load_dword v47, v[84:85], off
	global_load_dword v49, v[86:87], off
	global_load_dword v51, v[88:89], off
	global_load_dword v53, v[90:91], off
	global_load_dword v55, v[92:93], off
	global_load_dword v57, v[94:95], off
	global_load_dword v59, v[96:97], off
	global_load_dword v61, v[98:99], off
	global_load_dword v63, v[100:101], off
	global_load_dword v82, v[102:103], off
	global_load_dword v83, v[104:105], off
	global_load_dword v84, v[106:107], off
	global_load_dword v85, v[108:109], off
	global_load_dword v94, v[110:111], off
	global_load_dword v95, v[112:113], off
	global_load_dword v96, v[114:115], off
	global_load_dword v97, v[116:117], off
	global_load_dword v98, v[118:119], off
	global_load_dword v99, v[120:121], off
	global_load_dword v100, v[122:123], off
	global_load_dword v101, v[124:125], off
	global_load_dword v102, v[126:127], off
	global_load_dword v103, v[70:71], off
	global_load_dword v104, v[72:73], off
	global_load_dword v105, v[128:129], off offset:384
	global_load_dword v106, v[130:131], off offset:768
	global_load_dword v107, v[132:133], off offset:1152
	global_load_dword v108, v[74:75], off
	global_load_dword v109, v[76:77], off
	global_load_dword v110, v[78:79], off
	s_nop 0
	global_load_dword v80, v[80:81], off
	s_lshr_b32 s7, s7, 2
	s_add_i32 s7, s6, s7
	s_and_b32 s7, s7, -2.0
	v_add_u32_e32 v111, 0x800, v69
	s_sub_i32 s6, s6, s7
	v_add_u32_e32 v81, 0x400, v69
	v_add_u32_e32 v112, 0xc00, v69
	v_add_u32_e32 v113, 0x1000, v69
	v_add_u32_e32 v114, 0x1400, v69
	v_add_u32_e32 v115, 0x1800, v69
	v_add_u32_e32 v116, 0x1c00, v69
	v_or_b32_e32 v74, s6, v66
	v_or_b32_e32 v76, s6, v67
	v_or_b32_e32 v78, s6, v68
	v_ashrrev_i32_e32 v75, 31, v74
	v_ashrrev_i32_e32 v77, 31, v76
	v_ashrrev_i32_e32 v79, 31, v78
	v_lshl_add_u64 v[70:71], s[8:9], 1, v[4:5]
	v_lshlrev_b64 v[74:75], 13, v[74:75]
	v_lshlrev_b64 v[76:77], 13, v[76:77]
	v_lshlrev_b64 v[78:79], 13, v[78:79]
	v_lshl_add_u64 v[88:89], v[70:71], 0, v[74:75]
	v_lshl_add_u64 v[90:91], v[70:71], 0, v[76:77]
	v_lshl_add_u64 v[92:93], v[70:71], 0, v[78:79]
	v_or_b32_e32 v72, s6, v64
	v_ashrrev_i32_e32 v73, 31, v72
	v_lshlrev_b64 v[72:73], 13, v[72:73]
	v_lshl_add_u64 v[86:87], v[70:71], 0, v[72:73]
	s_add_i32 s24, s24, s76
	s_add_i32 s11, s11, s12
	s_ashr_i32 s6, s24, 31
	s_lshr_b32 s6, s6, 24
	s_add_i32 s6, s24, s6
	s_ashr_i32 s6, s6, 8
	s_lshl_b32 s8, s6, 6
	s_lshl_b32 s7, s6, 13
	s_mul_i32 s25, s6, 0x583000
	s_sub_i32 s6, s11, s7
	s_ashr_i32 s9, s8, 31
	s_mul_hi_i32 s7, s8, 0x160c0
	s_add_u32 s25, s40, s25
	s_addc_u32 s28, s41, s7
	s_ashr_i32 s7, s6, 31
	s_lshl_b64 s[26:27], s[6:7], 2
	s_add_u32 s26, s25, s26
	s_addc_u32 s27, s28, s27
	v_lshl_add_u64 v[134:135], s[26:27], 0, v[6:7]
	v_lshl_add_u64 v[136:137], v[134:135], 0, v[8:9]
	v_add_co_u32_e32 v192, vcc, s13, v136
	v_mov_b32_e32 v201, v3
	s_nop 0
	v_addc_co_u32_e32 v193, vcc, 0, v137, vcc
	v_add_co_u32_e32 v194, vcc, s14, v136
	v_mov_b32_e32 v203, v3
	s_nop 0
	v_addc_co_u32_e32 v195, vcc, 0, v137, vcc
	v_mov_b32_e32 v205, v3
	v_mov_b32_e32 v207, v3
	v_mov_b32_e32 v209, v3
	v_mov_b32_e32 v211, v3
	v_mov_b32_e32 v213, v3
	v_mov_b32_e32 v215, v3
	v_mov_b32_e32 v217, v3
; __device__ __forceinline__ void transpose_items(const float* W, int K, int ldw, int src0, int ncols, int blk, int mul, int add, bf16* WT, LAS float* scr, int gw, int NGW, int lane) {
;     ...
;     for (int it = gw; it < nitems; it += NGW) {
;         const int kb = it / nblk, nb = it - kb * nblk, k0 = 64 * kb, nl = 32 * nb;
;         const int drow = (nl / blk) * mul + (nl % blk) + add;
;         const float* src = W + (size_t)k0 * ldw + src0 + nl + (lane & 31);
;         float tv[32];
; #pragma unroll
;         for (int i = 0; i < 32; ++i) tv[i] = src[(size_t)(2 * i + (lane >> 5)) * ldw];
; #pragma unroll
;         for (int i = 0; i < 32; ++i) scr[(2 * i + (lane >> 5)) * 33 + (lane & 31)] = tv[i];
	v_mov_b32_e32 v219, v3
	v_lshl_add_u64 v[144:145], v[134:135], 0, v[16:17]
	v_lshl_add_u64 v[146:147], v[134:135], 0, v[18:19]
	v_lshl_add_u64 v[148:149], v[134:135], 0, v[20:21]
	v_lshl_add_u64 v[158:159], v[134:135], 0, v[30:31]
	v_lshl_add_u64 v[160:161], v[134:135], 0, v[32:33]
	v_lshl_add_u64 v[162:163], v[134:135], 0, v[34:35]
	v_lshl_add_u64 v[164:165], v[134:135], 0, v[36:37]
	v_lshl_add_u64 v[166:167], v[134:135], 0, v[38:39]
	v_lshl_add_u64 v[168:169], v[134:135], 0, v[40:41]
	v_lshl_add_u64 v[170:171], v[134:135], 0, v[42:43]
	v_lshl_add_u64 v[172:173], v[134:135], 0, v[2:3]
	v_lshl_add_u64 v[174:175], v[134:135], 0, v[200:201]
	v_add_co_u32_e32 v196, vcc, s15, v136
	v_lshl_add_u64 v[138:139], v[134:135], 0, v[10:11]
	v_lshl_add_u64 v[140:141], v[134:135], 0, v[12:13]
	v_lshl_add_u64 v[142:143], v[134:135], 0, v[14:15]
	v_lshl_add_u64 v[150:151], v[134:135], 0, v[22:23]
	v_lshl_add_u64 v[152:153], v[134:135], 0, v[24:25]
	v_lshl_add_u64 v[154:155], v[134:135], 0, v[26:27]
	v_lshl_add_u64 v[156:157], v[134:135], 0, v[28:29]
	v_lshl_add_u64 v[176:177], v[134:135], 0, v[202:203]
	v_lshl_add_u64 v[178:179], v[134:135], 0, v[204:205]
	v_lshl_add_u64 v[180:181], v[134:135], 0, v[206:207]
	v_lshl_add_u64 v[182:183], v[134:135], 0, v[208:209]
	v_lshl_add_u64 v[184:185], v[134:135], 0, v[210:211]
	v_lshl_add_u64 v[186:187], v[134:135], 0, v[212:213]
	v_lshl_add_u64 v[188:189], v[134:135], 0, v[214:215]
	v_lshl_add_u64 v[190:191], v[134:135], 0, v[216:217]
	v_lshl_add_u64 v[134:135], v[134:135], 0, v[218:219]
	v_addc_co_u32_e32 v197, vcc, 0, v137, vcc
	global_load_dword v201, v[146:147], off
	global_load_dword v203, v[148:149], off
	global_load_dword v205, v[150:151], off
	global_load_dword v207, v[152:153], off
	global_load_dword v209, v[154:155], off
	global_load_dword v211, v[156:157], off
	global_load_dword v213, v[158:159], off
	global_load_dword v215, v[160:161], off
	global_load_dword v217, v[162:163], off
	global_load_dword v219, v[164:165], off
	global_load_dword v146, v[166:167], off
	global_load_dword v147, v[168:169], off
	global_load_dword v148, v[170:171], off
	global_load_dword v149, v[172:173], off
	global_load_dword v158, v[174:175], off
	global_load_dword v159, v[176:177], off
	global_load_dword v160, v[178:179], off
	global_load_dword v161, v[180:181], off
	global_load_dword v162, v[182:183], off
	global_load_dword v163, v[184:185], off
	global_load_dword v164, v[186:187], off
	global_load_dword v165, v[188:189], off
	global_load_dword v166, v[190:191], off
	global_load_dword v167, v[134:135], off
	global_load_dword v168, v[136:137], off
	global_load_dword v169, v[192:193], off offset:384
	global_load_dword v170, v[194:195], off offset:768
	global_load_dword v171, v[196:197], off offset:1152
	global_load_dword v172, v[138:139], off
	global_load_dword v173, v[140:141], off
	global_load_dword v174, v[142:143], off
	s_nop 0
	global_load_dword v144, v[144:145], off
	s_lshr_b32 s7, s7, 2
	s_add_i32 s7, s6, s7
	s_and_b32 s7, s7, -2.0
	v_add_u32_e32 v175, 0x800, v69
	s_sub_i32 s6, s6, s7
	v_add_u32_e32 v145, 0x400, v69
	v_add_u32_e32 v176, 0xc00, v69
	v_add_u32_e32 v177, 0x1000, v69
	v_add_u32_e32 v178, 0x1400, v69
	v_add_u32_e32 v179, 0x1800, v69
	v_add_u32_e32 v180, 0x1c00, v69
	v_or_b32_e32 v138, s6, v66
	v_or_b32_e32 v140, s6, v67
	v_or_b32_e32 v142, s6, v68
	v_ashrrev_i32_e32 v139, 31, v138
	v_ashrrev_i32_e32 v141, 31, v140
	v_ashrrev_i32_e32 v143, 31, v142
	v_lshl_add_u64 v[134:135], s[8:9], 1, v[4:5]
	v_lshlrev_b64 v[138:139], 13, v[138:139]
	v_lshlrev_b64 v[140:141], 13, v[140:141]
	v_lshlrev_b64 v[142:143], 13, v[142:143]
	v_lshl_add_u64 v[152:153], v[134:135], 0, v[138:139]
	v_lshl_add_u64 v[154:155], v[134:135], 0, v[140:141]
	v_lshl_add_u64 v[156:157], v[134:135], 0, v[142:143]
	v_or_b32_e32 v136, s6, v64
	v_ashrrev_i32_e32 v137, 31, v136
	v_lshlrev_b64 v[136:137], 13, v[136:137]
	v_lshl_add_u64 v[150:151], v[134:135], 0, v[136:137]
	s_add_i32 s24, s24, s76
	s_add_i32 s11, s11, s12
	s_waitcnt vmcnt(62)
	ds_write2_b32 v111, v45, v47 offset0:16 offset1:82
	s_waitcnt vmcnt(60)
	ds_write2_b32 v111, v49, v51 offset0:148 offset1:214
	s_waitcnt vmcnt(58)
	ds_write2_b32 v112, v53, v55 offset0:24 offset1:90
	s_waitcnt vmcnt(56)
	ds_write2_b32 v112, v57, v59 offset0:156 offset1:222
	s_waitcnt vmcnt(54)
	ds_write2_b32 v113, v61, v63 offset0:32 offset1:98
	s_waitcnt vmcnt(52)
	ds_write2_b32 v113, v82, v83 offset0:164 offset1:230
	s_waitcnt vmcnt(50)
	ds_write2_b32 v114, v84, v85 offset0:40 offset1:106
	s_waitcnt vmcnt(48)
	ds_write2_b32 v114, v94, v95 offset0:172 offset1:238
	s_waitcnt vmcnt(46)
	ds_write2_b32 v115, v96, v97 offset0:48 offset1:114
	s_waitcnt vmcnt(44)
	ds_write2_b32 v115, v98, v99 offset0:180 offset1:246
	s_waitcnt vmcnt(42)
	ds_write2_b32 v116, v100, v101 offset0:56 offset1:122
	s_waitcnt vmcnt(40)
	ds_write2_b32 v116, v102, v103 offset0:188 offset1:254
	s_waitcnt vmcnt(38)
; #define LAS __attribute__((address_space(3)))
; #define LDS_WAIT() asm volatile("s_waitcnt lgkmcnt(0)" ::: "memory")
; __device__ __forceinline__ unsigned pk2(float lo, float hi) { const f32x2c v = {lo, hi}; return __builtin_bit_cast(unsigned, __builtin_convertvector(v, bf16x2c)); }
; __device__ __forceinline__ void transpose_items(const float* W, int K, int ldw, int src0, int ncols, int blk, int mul, int add, bf16* WT, LAS float* scr, int gw, int NGW, int lane) {
;     ...
; #pragma unroll
;         for (int i = 0; i < 32; ++i) scr[(2 * i + (lane >> 5)) * 33 + (lane & 31)] = tv[i];
;         LDS_WAIT(); asm volatile("" ::: "memory");
;         const int c = lane & 7;
; #pragma unroll
;         for (int j = 0; j < 4; ++j) { const int n = (lane >> 3) + 8 * j; const LAS float* s = scr + (8 * c) * 33 + n;
;             v4u o; o.x = pk2(s[0 * 33], s[1 * 33]); o.y = pk2(s[2 * 33], s[3 * 33]); o.z = pk2(s[4 * 33], s[5 * 33]); o.w = pk2(s[6 * 33], s[7 * 33]);
;             *(v4u*)(WT + (size_t)(drow + n) * K + k0 + 8 * c) = o; }
;         LDS_WAIT(); asm volatile("" ::: "memory");
	ds_write2_b32 v69, v104, v105 offset1:66
	s_waitcnt vmcnt(36)
	ds_write2_b32 v69, v106, v107 offset0:132 offset1:198
	s_waitcnt vmcnt(34)
	ds_write2_b32 v81, v108, v109 offset0:8 offset1:74
	s_waitcnt vmcnt(32)
	ds_write2_b32 v81, v110, v80 offset0:140 offset1:206
	s_waitcnt lgkmcnt(0)
	ds_read2_b32 v[74:75], v65 offset0:33 offset1:41
	ds_read2_b32 v[76:77], v65 offset1:8
	ds_read2_b32 v[78:79], v65 offset0:66 offset1:74
	ds_read2_b32 v[80:81], v65 offset0:99 offset1:107
	ds_read2_b32 v[82:83], v65 offset0:132 offset1:140
	ds_read2_b32 v[84:85], v65 offset0:165 offset1:173
	ds_read2_b32 v[94:95], v65 offset0:198 offset1:206
	ds_read2_b32 v[96:97], v65 offset0:231 offset1:239
	ds_read2_b32 v[98:99], v65 offset0:49 offset1:57
	ds_read2_b32 v[100:101], v65 offset0:16 offset1:24
	ds_read2_b32 v[102:103], v65 offset0:82 offset1:90
	ds_read2_b32 v[104:105], v65 offset0:115 offset1:123
	ds_read2_b32 v[106:107], v65 offset0:148 offset1:156
	ds_read2_b32 v[108:109], v65 offset0:181 offset1:189
	ds_read2_b32 v[110:111], v65 offset0:214 offset1:222
	ds_read2_b32 v[112:113], v65 offset0:247 offset1:255
	s_waitcnt lgkmcnt(0)
	v_cvt_pk_bf16_f32 v70, v76, v74
	v_cvt_pk_bf16_f32 v71, v78, v80
	v_cvt_pk_bf16_f32 v72, v82, v84
	v_cvt_pk_bf16_f32 v73, v94, v96
	v_cvt_pk_bf16_f32 v74, v77, v75
	v_cvt_pk_bf16_f32 v75, v79, v81
	v_cvt_pk_bf16_f32 v76, v83, v85
	v_cvt_pk_bf16_f32 v77, v95, v97
	v_cvt_pk_bf16_f32 v78, v100, v98
	v_cvt_pk_bf16_f32 v79, v102, v104
	v_cvt_pk_bf16_f32 v80, v106, v108
	v_cvt_pk_bf16_f32 v81, v110, v112
	v_cvt_pk_bf16_f32 v82, v101, v99
	v_cvt_pk_bf16_f32 v83, v103, v105
	v_cvt_pk_bf16_f32 v84, v107, v109
	v_cvt_pk_bf16_f32 v85, v111, v113
	global_store_dwordx4 v[86:87], v[70:73], off
	global_store_dwordx4 v[88:89], v[74:77], off
	global_store_dwordx4 v[90:91], v[78:81], off
	global_store_dwordx4 v[92:93], v[82:85], off
	s_waitcnt lgkmcnt(0)
	s_waitcnt vmcnt(34)
	ds_write2_b32 v175, v201, v203 offset0:16 offset1:82
	s_waitcnt vmcnt(32)
	ds_write2_b32 v175, v205, v207 offset0:148 offset1:214
	s_waitcnt vmcnt(30)
	ds_write2_b32 v176, v209, v211 offset0:24 offset1:90
	s_waitcnt vmcnt(28)
	ds_write2_b32 v176, v213, v215 offset0:156 offset1:222
	s_waitcnt vmcnt(26)
	ds_write2_b32 v177, v217, v219 offset0:32 offset1:98
	s_waitcnt vmcnt(24)
	ds_write2_b32 v177, v146, v147 offset0:164 offset1:230
	s_waitcnt vmcnt(22)
	ds_write2_b32 v178, v148, v149 offset0:40 offset1:106
	s_waitcnt vmcnt(20)
	ds_write2_b32 v178, v158, v159 offset0:172 offset1:238
	s_waitcnt vmcnt(18)
	ds_write2_b32 v179, v160, v161 offset0:48 offset1:114
	s_waitcnt vmcnt(16)
	ds_write2_b32 v179, v162, v163 offset0:180 offset1:246
	s_waitcnt vmcnt(14)
	ds_write2_b32 v180, v164, v165 offset0:56 offset1:122
	s_waitcnt vmcnt(12)
	ds_write2_b32 v180, v166, v167 offset0:188 offset1:254
	s_waitcnt vmcnt(10)
	ds_write2_b32 v69, v168, v169 offset1:66
	s_waitcnt vmcnt(8)
	ds_write2_b32 v69, v170, v171 offset0:132 offset1:198
	s_waitcnt vmcnt(6)
	ds_write2_b32 v145, v172, v173 offset0:8 offset1:74
	s_waitcnt vmcnt(4)
	ds_write2_b32 v145, v174, v144 offset0:140 offset1:206
	s_waitcnt lgkmcnt(0)
	ds_read2_b32 v[138:139], v65 offset0:33 offset1:41
	ds_read2_b32 v[140:141], v65 offset1:8
	ds_read2_b32 v[142:143], v65 offset0:66 offset1:74
	ds_read2_b32 v[144:145], v65 offset0:99 offset1:107
	ds_read2_b32 v[146:147], v65 offset0:132 offset1:140
	ds_read2_b32 v[148:149], v65 offset0:165 offset1:173
	ds_read2_b32 v[158:159], v65 offset0:198 offset1:206
	ds_read2_b32 v[160:161], v65 offset0:231 offset1:239
	ds_read2_b32 v[162:163], v65 offset0:49 offset1:57
	ds_read2_b32 v[164:165], v65 offset0:16 offset1:24
	ds_read2_b32 v[166:167], v65 offset0:82 offset1:90
	ds_read2_b32 v[168:169], v65 offset0:115 offset1:123
	ds_read2_b32 v[170:171], v65 offset0:148 offset1:156
	ds_read2_b32 v[172:173], v65 offset0:181 offset1:189
	ds_read2_b32 v[174:175], v65 offset0:214 offset1:222
	ds_read2_b32 v[176:177], v65 offset0:247 offset1:255
	s_waitcnt lgkmcnt(0)
	v_cvt_pk_bf16_f32 v134, v140, v138
	v_cvt_pk_bf16_f32 v135, v142, v144
	v_cvt_pk_bf16_f32 v136, v146, v148
	v_cvt_pk_bf16_f32 v137, v158, v160
	v_cvt_pk_bf16_f32 v138, v141, v139
	v_cvt_pk_bf16_f32 v139, v143, v145
	v_cvt_pk_bf16_f32 v140, v147, v149
	v_cvt_pk_bf16_f32 v141, v159, v161
	v_cvt_pk_bf16_f32 v142, v164, v162
	v_cvt_pk_bf16_f32 v143, v166, v168
	v_cvt_pk_bf16_f32 v144, v170, v172
	v_cvt_pk_bf16_f32 v145, v174, v176
	v_cvt_pk_bf16_f32 v146, v165, v163
	v_cvt_pk_bf16_f32 v147, v167, v169
	v_cvt_pk_bf16_f32 v148, v171, v173
	v_cvt_pk_bf16_f32 v149, v175, v177
	global_store_dwordx4 v[150:151], v[134:137], off
	global_store_dwordx4 v[152:153], v[138:141], off
	global_store_dwordx4 v[154:155], v[142:145], off
	global_store_dwordx4 v[156:157], v[146:149], off
	s_waitcnt lgkmcnt(0)
	s_cmpk_lt_i32 s24, 0x4000
	s_cbranch_scc1 .LBB0_90
	s_branch .Ltp90_done

; #define LAS __attribute__((address_space(3)))
; __device__ __forceinline__ void transpose_items(const float* W, int K, int ldw, int src0, int ncols, int blk, int mul, int add, bf16* WT, LAS float* scr, int gw, int NGW, int lane) {
;     const int nblk = ncols / 32, nitems = (K / 64) * nblk;
;     for (int it = gw; it < nitems; it += NGW) {
;         const int kb = it / nblk, nb = it - kb * nblk, k0 = 64 * kb, nl = 32 * nb;
;         const int drow = (nl / blk) * mul + (nl % blk) + add;
;         const float* src = W + (size_t)k0 * ldw + src0 + nl + (lane & 31);
; __global__ void __launch_bounds__(NWAVES * 64, 2) mk_fwd(Args args) {
;     ...
;         transpose_items(w_in, DM, N_IN, 0, 8192, 1 << 30, 0, 0, WIN, scr, gw, NGW, lane);
;         transpose_items(w_in, DM, N_IN, SC_QB, 6144, 1 << 30, 0, PC_QB, WIN, scr, gw, NGW, lane);
.Ltp90_done:
.LBB0_91:
	s_cmpk_gt_i32 s74, 0x2fff
	s_cbranch_scc1 .LBB0_94
	v_lshlrev_b32_e32 v2, 3, v0
	v_and_b32_e32 v2, 56, v2
	v_mov_b32_e32 v3, 0
	v_lshrrev_b32_e32 v64, 3, v198
	v_mul_u32_u24_e32 v8, 0x84, v2
	v_lshlrev_b32_e32 v2, 1, v2
	v_lshl_add_u64 v[4:5], s[78:79], 0, v[2:3]
	v_lshlrev_b32_e32 v2, 2, v64
	v_lshrrev_b32_e32 v7, 5, v198
	v_add3_u32 v65, s10, v8, v2
	s_movk_i32 s6, 0x5830
	v_mov_b32_e32 v8, 0x2c180
	v_mad_u32_u24 v10, v7, s6, v8
	v_mov_b32_e32 v8, 0x371e0
	v_mad_u32_u24 v12, v7, s6, v8
	v_mov_b32_e32 v8, 0x42240
	v_mad_u32_u24 v14, v7, s6, v8
	v_mov_b32_e32 v8, 0x4d2a0
	v_mad_u32_u24 v16, v7, s6, v8
	v_mov_b32_e32 v8, 0x58300
	v_mad_u32_u24 v18, v7, s6, v8
	v_mov_b32_e32 v8, 0x63360
	v_mad_u32_u24 v20, v7, s6, v8
	v_mov_b32_e32 v8, 0x6e3c0
	v_mad_u32_u24 v22, v7, s6, v8
	v_mov_b32_e32 v8, 0x79420
	v_mad_u32_u24 v24, v7, s6, v8
	v_mov_b32_e32 v8, 0x84480
	v_mad_u32_u24 v26, v7, s6, v8
	v_mov_b32_e32 v8, 0x8f4e0
	v_mad_u32_u24 v28, v7, s6, v8
	v_mov_b32_e32 v8, 0x9a540
	v_mad_u32_u24 v30, v7, s6, v8
	v_mov_b32_e32 v8, 0xa55a0
	v_mad_u32_u24 v32, v7, s6, v8
	v_mov_b32_e32 v8, 0xb0600
	v_mad_u32_u24 v34, v7, s6, v8
	v_mov_b32_e32 v8, 0xbb660
	v_mad_u32_u24 v36, v7, s6, v8
	v_mov_b32_e32 v8, 0xc66c0
	v_mad_u32_u24 v38, v7, s6, v8
	v_mov_b32_e32 v8, 0xd1720
	v_mad_u32_u24 v40, v7, s6, v8
	v_mov_b32_e32 v8, 0xdc780
	v_mad_u32_u24 v42, v7, s6, v8
	v_mov_b32_e32 v8, 0xe77e0
	v_mad_u32_u24 v44, v7, s6, v8
	v_mov_b32_e32 v8, 0xf2840
	v_mad_u32_u24 v46, v7, s6, v8
	v_mov_b32_e32 v8, 0xfd8a0
	v_mad_u32_u24 v48, v7, s6, v8
	v_mov_b32_e32 v8, 0x108900
	v_mad_u32_u24 v50, v7, s6, v8
	v_mov_b32_e32 v8, 0x113960
	v_mad_u32_u24 v52, v7, s6, v8
	v_mov_b32_e32 v8, 0x11e9c0
	v_mad_u32_u24 v54, v7, s6, v8
	v_mov_b32_e32 v8, 0x129a20
	v_mad_u32_u24 v56, v7, s6, v8
	v_mov_b32_e32 v8, 0x134a80
	v_readlane_b32 s36, v254, 7
	v_mad_u32_u24 v58, v7, s6, v8
	v_mov_b32_e32 v8, 0x13fae0
	v_readlane_b32 s40, v254, 11
	v_mad_u32_u24 v60, v7, s6, v8
	v_mov_b32_e32 v8, 0x14ab40
	v_readlane_b32 s41, v254, 12
	s_add_u32 s11, s40, 0x8080
	v_and_b32_e32 v6, 31, v0
	v_mad_u32_u24 v62, v7, s6, v8
	v_mov_b32_e32 v8, 0x155ba0
	v_readlane_b32 s7, v254, 0
	s_addc_u32 s12, s41, 0
	v_lshl_add_u32 v9, v6, 2, s10
	v_mul_u32_u24_e32 v2, 0x5830, v7
	v_mad_u32_u24 v70, v7, s6, v8
	v_mul_u32_u24_e32 v7, 0x84, v7
	s_lshl_b32 s6, s56, 8
	s_lshl_b32 s7, s7, 5
	v_or_b32_e32 v66, 8, v64
	v_or_b32_e32 v67, 16, v64
	v_or_b32_e32 v68, 24, v64
	s_add_i32 s13, s6, s7
	s_lshl_b32 s14, s72, 8
	v_lshlrev_b32_e32 v6, 2, v6
	v_lshlrev_b32_e32 v8, 2, v2
	s_mov_b32 s15, 0x2c000
	s_mov_b32 s24, 0x58000
	s_mov_b32 s25, 0x84000
	v_lshlrev_b32_e32 v10, 2, v10
	v_lshlrev_b32_e32 v12, 2, v12
	v_lshlrev_b32_e32 v14, 2, v14
	v_lshlrev_b32_e32 v16, 2, v16
	v_lshlrev_b32_e32 v18, 2, v18
	v_lshlrev_b32_e32 v20, 2, v20
	v_lshlrev_b32_e32 v22, 2, v22
	v_lshlrev_b32_e32 v24, 2, v24
	v_lshlrev_b32_e32 v26, 2, v26
	v_lshlrev_b32_e32 v28, 2, v28
	v_lshlrev_b32_e32 v30, 2, v30
	v_lshlrev_b32_e32 v32, 2, v32
	v_lshlrev_b32_e32 v34, 2, v34
	v_lshlrev_b32_e32 v36, 2, v36
	v_lshlrev_b32_e32 v38, 2, v38
	v_lshlrev_b32_e32 v40, 2, v40
	v_lshlrev_b32_e32 v42, 2, v42
	v_lshlrev_b32_e32 v2, 2, v44
	v_lshlrev_b32_e32 v44, 2, v46
	v_lshlrev_b32_e32 v46, 2, v48
	v_lshlrev_b32_e32 v48, 2, v50
	v_lshlrev_b32_e32 v50, 2, v52
	v_lshlrev_b32_e32 v52, 2, v54
	v_lshlrev_b32_e32 v54, 2, v56
	v_lshlrev_b32_e32 v56, 2, v58
	v_lshlrev_b32_e32 v58, 2, v60
	v_lshlrev_b32_e32 v60, 2, v62
	v_lshlrev_b32_e32 v62, 2, v70
	v_add_u32_e32 v69, v9, v7
	v_mov_b32_e32 v7, v3
	v_mov_b32_e32 v9, v3
	v_mov_b32_e32 v11, v3
	v_mov_b32_e32 v13, v3
	v_mov_b32_e32 v15, v3
	v_mov_b32_e32 v17, v3
	v_mov_b32_e32 v19, v3
	v_mov_b32_e32 v21, v3
	v_mov_b32_e32 v23, v3
	v_mov_b32_e32 v25, v3
	v_mov_b32_e32 v27, v3
	v_mov_b32_e32 v29, v3
	v_mov_b32_e32 v31, v3
	v_mov_b32_e32 v33, v3
	v_mov_b32_e32 v35, v3
	v_mov_b32_e32 v37, v3
	v_mov_b32_e32 v39, v3
	v_mov_b32_e32 v41, v3
	v_mov_b32_e32 v43, v3
	s_mov_b32 s26, s74
	v_readlane_b32 s37, v254, 8
	v_readlane_b32 s38, v254, 9
	v_readlane_b32 s39, v254, 10
	v_readlane_b32 s42, v254, 13
	v_readlane_b32 s43, v254, 14
	v_readlane_b32 s44, v254, 15
	v_readlane_b32 s45, v254, 16
	v_readlane_b32 s46, v254, 17
	v_readlane_b32 s47, v254, 18
	v_readlane_b32 s48, v254, 19
	v_readlane_b32 s49, v254, 20
	v_readlane_b32 s50, v254, 21
	v_readlane_b32 s51, v254, 22
